# lane-transposed epilogue stores (4 rows x 64B per quarter-wave) for MLP-up and last-layer down GEMMs, cvt_pk packing, prefetched residual
# speedup vs baseline: 1.0094x; 1.0073x over previous
.LBB0_1179:
	s_ashr_i32 s18, s56, 3
	v_lshl_add_u32 v172, s56, 8, v176
	s_ashr_i32 s19, s18, 31
	v_ashrrev_i32_e32 v173, 31, v172
	s_lshl_b64 s[18:19], s[18:19], 12
	v_lshl_add_u64 v[170:171], v[172:173], 2, s[54:55]
	s_cmpk_lt_i32 s56, 0x80
	global_load_dword v158, v[170:171], off
	global_load_dword v184, v[170:171], off offset:64
	global_load_dword v185, v[170:171], off offset:128
	global_load_dword v186, v[170:171], off offset:192
	global_load_dword v187, v[170:171], off offset:512
	global_load_dword v188, v[170:171], off offset:576
	global_load_dword v189, v[170:171], off offset:640
	global_load_dword v190, v[170:171], off offset:704
	s_cselect_b32 s19, s19, 0
	s_cselect_b32 s18, s18, 0x10000
	s_lshl_b64 s[18:19], s[18:19], 2
	v_lshl_or_b32 v154, s89, 8, v178
	s_add_u32 s18, s35, s18
	s_addc_u32 s19, s50, s19
	v_ashrrev_i32_e32 v155, 31, v154
	v_lshl_add_u64 v[72:73], v[154:155], 2, s[18:19]
	global_load_dwordx4 v[84:87], v[72:73], off
	global_load_dwordx4 v[80:83], v[72:73], off offset:16
	global_load_dwordx4 v[76:79], v[72:73], off offset:512
	s_nop 0
	global_load_dwordx4 v[72:75], v[72:73], off offset:528
	v_lshlrev_b64 v[156:157], 13, v[172:173]
	v_lshlrev_b64 v[174:175], 1, v[154:155]
	v_lshl_add_u64 v[154:155], s[70:71], 0, v[156:157]
	v_lshl_add_u64 v[168:169], v[154:155], 0, v[174:175]
	s_mov_b32 s11, 0x100000
	s_mov_b64 s[18:19], 0x100000
	v_readlane_b32 s94, v255, 32
	v_readlane_b32 s95, v255, 33
	s_waitcnt vmcnt(0)
	v_mbcnt_lo_u32_b32 v193, -1, 0
	v_mbcnt_hi_u32_b32 v193, -1, v193
	v_and_b32_e32 v194, 15, v193
	v_lshrrev_b32_e32 v195, 2, v193
	v_sub_u32_e32 v195, v195, v194
	v_add_u32_e32 v195, v172, v195
	v_lshrrev_b32_e32 v196, 4, v193
	v_and_b32_e32 v197, 3, v193
	v_sub_u32_e32 v197, v197, v196
	v_lshl_add_u32 v197, v197, 4, v174
	v_lshl_add_u32 v191, v195, 13, v197
	v_and_b32_e32 v198, 3, v193
	v_lshrrev_b32_e32 v199, 2, v193
	v_lshl_add_u32 v198, v198, 4, v199
	v_lshlrev_b32_e32 v198, 2, v198
	s_mov_b64 s[18:19], s[70:71]
	v_fmamk_f32 v158, v158, 0x3a800000, v228
	v_fmamk_f32 v184, v184, 0x3a800000, v228
	v_fmamk_f32 v185, v185, 0x3a800000, v228
	v_fmamk_f32 v186, v186, 0x3a800000, v228
	v_fmamk_f32 v187, v187, 0x3a800000, v228
	v_fmamk_f32 v188, v188, 0x3a800000, v228
	v_fmamk_f32 v189, v189, 0x3a800000, v228
	v_fmamk_f32 v190, v190, 0x3a800000, v228
	v_rsq_f32_e32 v158, v158
	v_rsq_f32_e32 v184, v184
	v_rsq_f32_e32 v185, v185
	v_rsq_f32_e32 v186, v186
	v_rsq_f32_e32 v187, v187
	v_rsq_f32_e32 v188, v188
	v_rsq_f32_e32 v189, v189
	v_rsq_f32_e32 v190, v190
	s_nop 0
	v_mov_b32_e32 v192, v158
	v_pk_fma_f32 v[140:141], v[140:141], v[192:193], v[84:85] op_sel_hi:[1,0,1]
	v_pk_fma_f32 v[142:143], v[142:143], v[192:193], v[86:87] op_sel_hi:[1,0,1]
	v_pk_fma_f32 v[136:137], v[136:137], v[192:193], v[80:81] op_sel_hi:[1,0,1]
	v_pk_fma_f32 v[138:139], v[138:139], v[192:193], v[82:83] op_sel_hi:[1,0,1]
	v_pk_fma_f32 v[132:133], v[132:133], v[192:193], v[76:77] op_sel_hi:[1,0,1]
	v_pk_fma_f32 v[134:135], v[134:135], v[192:193], v[78:79] op_sel_hi:[1,0,1]
	v_pk_fma_f32 v[128:129], v[128:129], v[192:193], v[72:73] op_sel_hi:[1,0,1]
	v_pk_fma_f32 v[130:131], v[130:131], v[192:193], v[74:75] op_sel_hi:[1,0,1]
	v_max_f32_e32 v140, 0, v140
	v_max_f32_e32 v141, 0, v141
	v_max_f32_e32 v142, 0, v142
	v_max_f32_e32 v143, 0, v143
	v_max_f32_e32 v136, 0, v136
	v_max_f32_e32 v137, 0, v137
	v_max_f32_e32 v138, 0, v138
	v_max_f32_e32 v139, 0, v139
	v_max_f32_e32 v132, 0, v132
	v_max_f32_e32 v133, 0, v133
	v_max_f32_e32 v134, 0, v134
	v_max_f32_e32 v135, 0, v135
	v_max_f32_e32 v128, 0, v128
	v_max_f32_e32 v129, 0, v129
	v_max_f32_e32 v130, 0, v130
	v_max_f32_e32 v131, 0, v131
	v_pk_mul_f32 v[140:141], v[140:141], v[140:141]
	v_pk_mul_f32 v[142:143], v[142:143], v[142:143]
	v_pk_mul_f32 v[136:137], v[136:137], v[136:137]
	v_pk_mul_f32 v[138:139], v[138:139], v[138:139]
	v_pk_mul_f32 v[132:133], v[132:133], v[132:133]
	v_pk_mul_f32 v[134:135], v[134:135], v[134:135]
	v_pk_mul_f32 v[128:129], v[128:129], v[128:129]
	v_pk_mul_f32 v[130:131], v[130:131], v[130:131]
	v_cvt_pk_bf16_f32 v140, v140, v141
	v_cvt_pk_bf16_f32 v141, v142, v143
	v_cvt_pk_bf16_f32 v142, v136, v137
	v_cvt_pk_bf16_f32 v143, v138, v139
	v_cvt_pk_bf16_f32 v132, v132, v133
	v_cvt_pk_bf16_f32 v133, v134, v135
	v_cvt_pk_bf16_f32 v134, v128, v129
	v_cvt_pk_bf16_f32 v135, v130, v131
	ds_bpermute_b32 v216, v198, v140
	ds_bpermute_b32 v217, v198, v141
	ds_bpermute_b32 v218, v198, v142
	ds_bpermute_b32 v219, v198, v143
	ds_bpermute_b32 v220, v198, v132
	ds_bpermute_b32 v221, v198, v133
	ds_bpermute_b32 v222, v198, v134
	ds_bpermute_b32 v223, v198, v135
	v_mov_b32_e32 v192, v184
	v_pk_fma_f32 v[124:125], v[124:125], v[192:193], v[84:85] op_sel_hi:[1,0,1]
	v_pk_fma_f32 v[126:127], v[126:127], v[192:193], v[86:87] op_sel_hi:[1,0,1]
	v_pk_fma_f32 v[120:121], v[120:121], v[192:193], v[80:81] op_sel_hi:[1,0,1]
	v_pk_fma_f32 v[122:123], v[122:123], v[192:193], v[82:83] op_sel_hi:[1,0,1]
	v_pk_fma_f32 v[116:117], v[116:117], v[192:193], v[76:77] op_sel_hi:[1,0,1]
	v_pk_fma_f32 v[118:119], v[118:119], v[192:193], v[78:79] op_sel_hi:[1,0,1]
	v_pk_fma_f32 v[112:113], v[112:113], v[192:193], v[72:73] op_sel_hi:[1,0,1]
	v_pk_fma_f32 v[114:115], v[114:115], v[192:193], v[74:75] op_sel_hi:[1,0,1]
	v_max_f32_e32 v124, 0, v124
	v_max_f32_e32 v125, 0, v125
	v_max_f32_e32 v126, 0, v126
	v_max_f32_e32 v127, 0, v127
	v_max_f32_e32 v120, 0, v120
	v_max_f32_e32 v121, 0, v121
	v_max_f32_e32 v122, 0, v122
	v_max_f32_e32 v123, 0, v123
	v_max_f32_e32 v116, 0, v116
	v_max_f32_e32 v117, 0, v117
	v_max_f32_e32 v118, 0, v118
	v_max_f32_e32 v119, 0, v119
	v_max_f32_e32 v112, 0, v112
	v_max_f32_e32 v113, 0, v113
	v_max_f32_e32 v114, 0, v114
	v_max_f32_e32 v115, 0, v115
	v_pk_mul_f32 v[124:125], v[124:125], v[124:125]
	v_pk_mul_f32 v[126:127], v[126:127], v[126:127]
	v_pk_mul_f32 v[120:121], v[120:121], v[120:121]
	v_pk_mul_f32 v[122:123], v[122:123], v[122:123]
	v_pk_mul_f32 v[116:117], v[116:117], v[116:117]
	v_pk_mul_f32 v[118:119], v[118:119], v[118:119]
	v_pk_mul_f32 v[112:113], v[112:113], v[112:113]
	v_pk_mul_f32 v[114:115], v[114:115], v[114:115]
	v_cvt_pk_bf16_f32 v124, v124, v125
	v_cvt_pk_bf16_f32 v125, v126, v127
	v_cvt_pk_bf16_f32 v126, v120, v121
	v_cvt_pk_bf16_f32 v127, v122, v123
	v_cvt_pk_bf16_f32 v116, v116, v117
	v_cvt_pk_bf16_f32 v117, v118, v119
	v_cvt_pk_bf16_f32 v118, v112, v113
	v_cvt_pk_bf16_f32 v119, v114, v115
	ds_bpermute_b32 v208, v198, v124
	ds_bpermute_b32 v209, v198, v125
	ds_bpermute_b32 v210, v198, v126
	ds_bpermute_b32 v211, v198, v127
	s_waitcnt lgkmcnt(4)
	global_store_dwordx4 v191, v[216:219], s[18:19]
	global_store_dwordx4 v191, v[220:223], s[18:19] offset:256
	s_add_u32 s18, s18, 0x20000
	s_addc_u32 s19, s19, 0
	ds_bpermute_b32 v212, v198, v116
	ds_bpermute_b32 v213, v198, v117
	ds_bpermute_b32 v214, v198, v118
	ds_bpermute_b32 v215, v198, v119
	v_mov_b32_e32 v192, v185
	v_pk_fma_f32 v[108:109], v[108:109], v[192:193], v[84:85] op_sel_hi:[1,0,1]
	v_pk_fma_f32 v[110:111], v[110:111], v[192:193], v[86:87] op_sel_hi:[1,0,1]
	v_pk_fma_f32 v[104:105], v[104:105], v[192:193], v[80:81] op_sel_hi:[1,0,1]
	v_pk_fma_f32 v[106:107], v[106:107], v[192:193], v[82:83] op_sel_hi:[1,0,1]
	v_pk_fma_f32 v[100:101], v[100:101], v[192:193], v[76:77] op_sel_hi:[1,0,1]
	v_pk_fma_f32 v[102:103], v[102:103], v[192:193], v[78:79] op_sel_hi:[1,0,1]
	v_pk_fma_f32 v[96:97], v[96:97], v[192:193], v[72:73] op_sel_hi:[1,0,1]
	v_pk_fma_f32 v[98:99], v[98:99], v[192:193], v[74:75] op_sel_hi:[1,0,1]
	v_max_f32_e32 v108, 0, v108
	v_max_f32_e32 v109, 0, v109
	v_max_f32_e32 v110, 0, v110
	v_max_f32_e32 v111, 0, v111
	v_max_f32_e32 v104, 0, v104
	v_max_f32_e32 v105, 0, v105
	v_max_f32_e32 v106, 0, v106
	v_max_f32_e32 v107, 0, v107
	v_max_f32_e32 v100, 0, v100
	v_max_f32_e32 v101, 0, v101
	v_max_f32_e32 v102, 0, v102
	v_max_f32_e32 v103, 0, v103
	v_max_f32_e32 v96, 0, v96
	v_max_f32_e32 v97, 0, v97
	v_max_f32_e32 v98, 0, v98
	v_max_f32_e32 v99, 0, v99
	v_pk_mul_f32 v[108:109], v[108:109], v[108:109]
	v_pk_mul_f32 v[110:111], v[110:111], v[110:111]
	v_pk_mul_f32 v[104:105], v[104:105], v[104:105]
	v_pk_mul_f32 v[106:107], v[106:107], v[106:107]
	v_pk_mul_f32 v[100:101], v[100:101], v[100:101]
	v_pk_mul_f32 v[102:103], v[102:103], v[102:103]
	v_pk_mul_f32 v[96:97], v[96:97], v[96:97]
	v_pk_mul_f32 v[98:99], v[98:99], v[98:99]
	v_cvt_pk_bf16_f32 v108, v108, v109
	v_cvt_pk_bf16_f32 v109, v110, v111
	v_cvt_pk_bf16_f32 v110, v104, v105
	v_cvt_pk_bf16_f32 v111, v106, v107
	v_cvt_pk_bf16_f32 v100, v100, v101
	v_cvt_pk_bf16_f32 v101, v102, v103
	v_cvt_pk_bf16_f32 v102, v96, v97
	v_cvt_pk_bf16_f32 v103, v98, v99
	ds_bpermute_b32 v216, v198, v108
	ds_bpermute_b32 v217, v198, v109
	ds_bpermute_b32 v218, v198, v110
	ds_bpermute_b32 v219, v198, v111
	s_waitcnt lgkmcnt(4)
	global_store_dwordx4 v191, v[208:211], s[18:19]
	global_store_dwordx4 v191, v[212:215], s[18:19] offset:256
	s_add_u32 s18, s18, 0x20000
	s_addc_u32 s19, s19, 0
	ds_bpermute_b32 v220, v198, v100
	ds_bpermute_b32 v221, v198, v101
	ds_bpermute_b32 v222, v198, v102
	ds_bpermute_b32 v223, v198, v103
	v_mov_b32_e32 v192, v186
	v_pk_fma_f32 v[92:93], v[92:93], v[192:193], v[84:85] op_sel_hi:[1,0,1]
	v_pk_fma_f32 v[94:95], v[94:95], v[192:193], v[86:87] op_sel_hi:[1,0,1]
	v_pk_fma_f32 v[88:89], v[88:89], v[192:193], v[80:81] op_sel_hi:[1,0,1]
	v_pk_fma_f32 v[90:91], v[90:91], v[192:193], v[82:83] op_sel_hi:[1,0,1]
	v_pk_fma_f32 v[68:69], v[68:69], v[192:193], v[76:77] op_sel_hi:[1,0,1]
	v_pk_fma_f32 v[70:71], v[70:71], v[192:193], v[78:79] op_sel_hi:[1,0,1]
	v_pk_fma_f32 v[64:65], v[64:65], v[192:193], v[72:73] op_sel_hi:[1,0,1]
	v_pk_fma_f32 v[66:67], v[66:67], v[192:193], v[74:75] op_sel_hi:[1,0,1]
	v_max_f32_e32 v92, 0, v92
	v_max_f32_e32 v93, 0, v93
	v_max_f32_e32 v94, 0, v94
	v_max_f32_e32 v95, 0, v95
	v_max_f32_e32 v88, 0, v88
	v_max_f32_e32 v89, 0, v89
	v_max_f32_e32 v90, 0, v90
	v_max_f32_e32 v91, 0, v91
	v_max_f32_e32 v68, 0, v68
	v_max_f32_e32 v69, 0, v69
	v_max_f32_e32 v70, 0, v70
	v_max_f32_e32 v71, 0, v71
	v_max_f32_e32 v64, 0, v64
	v_max_f32_e32 v65, 0, v65
	v_max_f32_e32 v66, 0, v66
	v_max_f32_e32 v67, 0, v67
	v_pk_mul_f32 v[92:93], v[92:93], v[92:93]
	v_pk_mul_f32 v[94:95], v[94:95], v[94:95]
	v_pk_mul_f32 v[88:89], v[88:89], v[88:89]
	v_pk_mul_f32 v[90:91], v[90:91], v[90:91]
	v_pk_mul_f32 v[68:69], v[68:69], v[68:69]
	v_pk_mul_f32 v[70:71], v[70:71], v[70:71]
	v_pk_mul_f32 v[64:65], v[64:65], v[64:65]
	v_pk_mul_f32 v[66:67], v[66:67], v[66:67]
	v_cvt_pk_bf16_f32 v92, v92, v93
	v_cvt_pk_bf16_f32 v93, v94, v95
	v_cvt_pk_bf16_f32 v94, v88, v89
	v_cvt_pk_bf16_f32 v95, v90, v91
	v_cvt_pk_bf16_f32 v68, v68, v69
	v_cvt_pk_bf16_f32 v69, v70, v71
	v_cvt_pk_bf16_f32 v70, v64, v65
	v_cvt_pk_bf16_f32 v71, v66, v67
	ds_bpermute_b32 v208, v198, v92
	ds_bpermute_b32 v209, v198, v93
	ds_bpermute_b32 v210, v198, v94
	ds_bpermute_b32 v211, v198, v95
	s_waitcnt lgkmcnt(4)
	global_store_dwordx4 v191, v[216:219], s[18:19]
	global_store_dwordx4 v191, v[220:223], s[18:19] offset:256
	s_add_u32 s18, s18, 0x20000
	s_addc_u32 s19, s19, 0
	ds_bpermute_b32 v212, v198, v68
	ds_bpermute_b32 v213, v198, v69
	ds_bpermute_b32 v214, v198, v70
	ds_bpermute_b32 v215, v198, v71
	v_mov_b32_e32 v192, v187
	v_pk_fma_f32 v[60:61], v[60:61], v[192:193], v[84:85] op_sel_hi:[1,0,1]
	v_pk_fma_f32 v[62:63], v[62:63], v[192:193], v[86:87] op_sel_hi:[1,0,1]
	v_pk_fma_f32 v[56:57], v[56:57], v[192:193], v[80:81] op_sel_hi:[1,0,1]
	v_pk_fma_f32 v[58:59], v[58:59], v[192:193], v[82:83] op_sel_hi:[1,0,1]
	v_pk_fma_f32 v[52:53], v[52:53], v[192:193], v[76:77] op_sel_hi:[1,0,1]
	v_pk_fma_f32 v[54:55], v[54:55], v[192:193], v[78:79] op_sel_hi:[1,0,1]
	v_pk_fma_f32 v[48:49], v[48:49], v[192:193], v[72:73] op_sel_hi:[1,0,1]
	v_pk_fma_f32 v[50:51], v[50:51], v[192:193], v[74:75] op_sel_hi:[1,0,1]
	v_max_f32_e32 v60, 0, v60
	v_max_f32_e32 v61, 0, v61
	v_max_f32_e32 v62, 0, v62
	v_max_f32_e32 v63, 0, v63
	v_max_f32_e32 v56, 0, v56
	v_max_f32_e32 v57, 0, v57
	v_max_f32_e32 v58, 0, v58
	v_max_f32_e32 v59, 0, v59
	v_max_f32_e32 v52, 0, v52
	v_max_f32_e32 v53, 0, v53
	v_max_f32_e32 v54, 0, v54
	v_max_f32_e32 v55, 0, v55
	v_max_f32_e32 v48, 0, v48
	v_max_f32_e32 v49, 0, v49
	v_max_f32_e32 v50, 0, v50
	v_max_f32_e32 v51, 0, v51
	v_pk_mul_f32 v[60:61], v[60:61], v[60:61]
	v_pk_mul_f32 v[62:63], v[62:63], v[62:63]
	v_pk_mul_f32 v[56:57], v[56:57], v[56:57]
	v_pk_mul_f32 v[58:59], v[58:59], v[58:59]
	v_pk_mul_f32 v[52:53], v[52:53], v[52:53]
	v_pk_mul_f32 v[54:55], v[54:55], v[54:55]
	v_pk_mul_f32 v[48:49], v[48:49], v[48:49]
	v_pk_mul_f32 v[50:51], v[50:51], v[50:51]
	v_cvt_pk_bf16_f32 v60, v60, v61
	v_cvt_pk_bf16_f32 v61, v62, v63
	v_cvt_pk_bf16_f32 v62, v56, v57
	v_cvt_pk_bf16_f32 v63, v58, v59
	v_cvt_pk_bf16_f32 v52, v52, v53
	v_cvt_pk_bf16_f32 v53, v54, v55
	v_cvt_pk_bf16_f32 v54, v48, v49
	v_cvt_pk_bf16_f32 v55, v50, v51
	ds_bpermute_b32 v216, v198, v60
	ds_bpermute_b32 v217, v198, v61
	ds_bpermute_b32 v218, v198, v62
	ds_bpermute_b32 v219, v198, v63
	s_waitcnt lgkmcnt(4)
	global_store_dwordx4 v191, v[208:211], s[18:19]
	global_store_dwordx4 v191, v[212:215], s[18:19] offset:256
	s_add_u32 s18, s18, 0xa0000
	s_addc_u32 s19, s19, 0
	ds_bpermute_b32 v220, v198, v52
	ds_bpermute_b32 v221, v198, v53
	ds_bpermute_b32 v222, v198, v54
	ds_bpermute_b32 v223, v198, v55
	v_mov_b32_e32 v192, v188
	v_pk_fma_f32 v[44:45], v[44:45], v[192:193], v[84:85] op_sel_hi:[1,0,1]
	v_pk_fma_f32 v[46:47], v[46:47], v[192:193], v[86:87] op_sel_hi:[1,0,1]
	v_pk_fma_f32 v[40:41], v[40:41], v[192:193], v[80:81] op_sel_hi:[1,0,1]
	v_pk_fma_f32 v[42:43], v[42:43], v[192:193], v[82:83] op_sel_hi:[1,0,1]
	v_pk_fma_f32 v[36:37], v[36:37], v[192:193], v[76:77] op_sel_hi:[1,0,1]
	v_pk_fma_f32 v[38:39], v[38:39], v[192:193], v[78:79] op_sel_hi:[1,0,1]
	v_pk_fma_f32 v[32:33], v[32:33], v[192:193], v[72:73] op_sel_hi:[1,0,1]
	v_pk_fma_f32 v[34:35], v[34:35], v[192:193], v[74:75] op_sel_hi:[1,0,1]
	v_max_f32_e32 v44, 0, v44
	v_max_f32_e32 v45, 0, v45
	v_max_f32_e32 v46, 0, v46
	v_max_f32_e32 v47, 0, v47
	v_max_f32_e32 v40, 0, v40
	v_max_f32_e32 v41, 0, v41
	v_max_f32_e32 v42, 0, v42
	v_max_f32_e32 v43, 0, v43
	v_max_f32_e32 v36, 0, v36
	v_max_f32_e32 v37, 0, v37
	v_max_f32_e32 v38, 0, v38
	v_max_f32_e32 v39, 0, v39
	v_max_f32_e32 v32, 0, v32
	v_max_f32_e32 v33, 0, v33
	v_max_f32_e32 v34, 0, v34
	v_max_f32_e32 v35, 0, v35
	v_pk_mul_f32 v[44:45], v[44:45], v[44:45]
	v_pk_mul_f32 v[46:47], v[46:47], v[46:47]
	v_pk_mul_f32 v[40:41], v[40:41], v[40:41]
	v_pk_mul_f32 v[42:43], v[42:43], v[42:43]
	v_pk_mul_f32 v[36:37], v[36:37], v[36:37]
	v_pk_mul_f32 v[38:39], v[38:39], v[38:39]
	v_pk_mul_f32 v[32:33], v[32:33], v[32:33]
	v_pk_mul_f32 v[34:35], v[34:35], v[34:35]
	v_cvt_pk_bf16_f32 v44, v44, v45
	v_cvt_pk_bf16_f32 v45, v46, v47
	v_cvt_pk_bf16_f32 v46, v40, v41
	v_cvt_pk_bf16_f32 v47, v42, v43
	v_cvt_pk_bf16_f32 v36, v36, v37
	v_cvt_pk_bf16_f32 v37, v38, v39
	v_cvt_pk_bf16_f32 v38, v32, v33
	v_cvt_pk_bf16_f32 v39, v34, v35
	ds_bpermute_b32 v208, v198, v44
	ds_bpermute_b32 v209, v198, v45
	ds_bpermute_b32 v210, v198, v46
	ds_bpermute_b32 v211, v198, v47
	s_waitcnt lgkmcnt(4)
	global_store_dwordx4 v191, v[216:219], s[18:19]
	global_store_dwordx4 v191, v[220:223], s[18:19] offset:256
	s_add_u32 s18, s18, 0x20000
	s_addc_u32 s19, s19, 0
	ds_bpermute_b32 v212, v198, v36
	ds_bpermute_b32 v213, v198, v37
	ds_bpermute_b32 v214, v198, v38
	ds_bpermute_b32 v215, v198, v39
	v_mov_b32_e32 v192, v189
	v_pk_fma_f32 v[28:29], v[28:29], v[192:193], v[84:85] op_sel_hi:[1,0,1]
	v_pk_fma_f32 v[30:31], v[30:31], v[192:193], v[86:87] op_sel_hi:[1,0,1]
	v_pk_fma_f32 v[24:25], v[24:25], v[192:193], v[80:81] op_sel_hi:[1,0,1]
	v_pk_fma_f32 v[26:27], v[26:27], v[192:193], v[82:83] op_sel_hi:[1,0,1]
	v_pk_fma_f32 v[20:21], v[20:21], v[192:193], v[76:77] op_sel_hi:[1,0,1]
	v_pk_fma_f32 v[22:23], v[22:23], v[192:193], v[78:79] op_sel_hi:[1,0,1]
	v_pk_fma_f32 v[16:17], v[16:17], v[192:193], v[72:73] op_sel_hi:[1,0,1]
	v_pk_fma_f32 v[18:19], v[18:19], v[192:193], v[74:75] op_sel_hi:[1,0,1]
	v_max_f32_e32 v28, 0, v28
	v_max_f32_e32 v29, 0, v29
	v_max_f32_e32 v30, 0, v30
	v_max_f32_e32 v31, 0, v31
	v_max_f32_e32 v24, 0, v24
	v_max_f32_e32 v25, 0, v25
	v_max_f32_e32 v26, 0, v26
	v_max_f32_e32 v27, 0, v27
	v_max_f32_e32 v20, 0, v20
	v_max_f32_e32 v21, 0, v21
	v_max_f32_e32 v22, 0, v22
	v_max_f32_e32 v23, 0, v23
	v_max_f32_e32 v16, 0, v16
	v_max_f32_e32 v17, 0, v17
	v_max_f32_e32 v18, 0, v18
	v_max_f32_e32 v19, 0, v19
	v_pk_mul_f32 v[28:29], v[28:29], v[28:29]
	v_pk_mul_f32 v[30:31], v[30:31], v[30:31]
	v_pk_mul_f32 v[24:25], v[24:25], v[24:25]
	v_pk_mul_f32 v[26:27], v[26:27], v[26:27]
	v_pk_mul_f32 v[20:21], v[20:21], v[20:21]
	v_pk_mul_f32 v[22:23], v[22:23], v[22:23]
	v_pk_mul_f32 v[16:17], v[16:17], v[16:17]
	v_pk_mul_f32 v[18:19], v[18:19], v[18:19]
	v_cvt_pk_bf16_f32 v28, v28, v29
	v_cvt_pk_bf16_f32 v29, v30, v31
	v_cvt_pk_bf16_f32 v30, v24, v25
	v_cvt_pk_bf16_f32 v31, v26, v27
	v_cvt_pk_bf16_f32 v20, v20, v21
	v_cvt_pk_bf16_f32 v21, v22, v23
	v_cvt_pk_bf16_f32 v22, v16, v17
	v_cvt_pk_bf16_f32 v23, v18, v19
	ds_bpermute_b32 v216, v198, v28
	ds_bpermute_b32 v217, v198, v29
	ds_bpermute_b32 v218, v198, v30
	ds_bpermute_b32 v219, v198, v31
	s_waitcnt lgkmcnt(4)
	global_store_dwordx4 v191, v[208:211], s[18:19]
	global_store_dwordx4 v191, v[212:215], s[18:19] offset:256
	s_add_u32 s18, s18, 0x20000
	s_addc_u32 s19, s19, 0
	ds_bpermute_b32 v220, v198, v20
	ds_bpermute_b32 v221, v198, v21
	ds_bpermute_b32 v222, v198, v22
	ds_bpermute_b32 v223, v198, v23
	v_mov_b32_e32 v192, v190
	v_pk_fma_f32 v[12:13], v[12:13], v[192:193], v[84:85] op_sel_hi:[1,0,1]
	v_pk_fma_f32 v[14:15], v[14:15], v[192:193], v[86:87] op_sel_hi:[1,0,1]
	v_pk_fma_f32 v[8:9], v[8:9], v[192:193], v[80:81] op_sel_hi:[1,0,1]
	v_pk_fma_f32 v[10:11], v[10:11], v[192:193], v[82:83] op_sel_hi:[1,0,1]
	v_pk_fma_f32 v[4:5], v[4:5], v[192:193], v[76:77] op_sel_hi:[1,0,1]
	v_pk_fma_f32 v[6:7], v[6:7], v[192:193], v[78:79] op_sel_hi:[1,0,1]
	v_pk_fma_f32 v[0:1], v[0:1], v[192:193], v[72:73] op_sel_hi:[1,0,1]
	v_pk_fma_f32 v[2:3], v[2:3], v[192:193], v[74:75] op_sel_hi:[1,0,1]
	v_max_f32_e32 v12, 0, v12
	v_max_f32_e32 v13, 0, v13
	v_max_f32_e32 v14, 0, v14
	v_max_f32_e32 v15, 0, v15
	v_max_f32_e32 v8, 0, v8
	v_max_f32_e32 v9, 0, v9
	v_max_f32_e32 v10, 0, v10
	v_max_f32_e32 v11, 0, v11
	v_max_f32_e32 v4, 0, v4
	v_max_f32_e32 v5, 0, v5
	v_max_f32_e32 v6, 0, v6
	v_max_f32_e32 v7, 0, v7
	v_max_f32_e32 v0, 0, v0
	v_max_f32_e32 v1, 0, v1
	v_max_f32_e32 v2, 0, v2
	v_max_f32_e32 v3, 0, v3
	v_pk_mul_f32 v[12:13], v[12:13], v[12:13]
	v_pk_mul_f32 v[14:15], v[14:15], v[14:15]
	v_pk_mul_f32 v[8:9], v[8:9], v[8:9]
	v_pk_mul_f32 v[10:11], v[10:11], v[10:11]
	v_pk_mul_f32 v[4:5], v[4:5], v[4:5]
	v_pk_mul_f32 v[6:7], v[6:7], v[6:7]
	v_pk_mul_f32 v[0:1], v[0:1], v[0:1]
	v_pk_mul_f32 v[2:3], v[2:3], v[2:3]
	v_cvt_pk_bf16_f32 v12, v12, v13
	v_cvt_pk_bf16_f32 v13, v14, v15
	v_cvt_pk_bf16_f32 v14, v8, v9
	v_cvt_pk_bf16_f32 v15, v10, v11
	v_cvt_pk_bf16_f32 v4, v4, v5
	v_cvt_pk_bf16_f32 v5, v6, v7
	v_cvt_pk_bf16_f32 v6, v0, v1
	v_cvt_pk_bf16_f32 v7, v2, v3
	ds_bpermute_b32 v208, v198, v12
	ds_bpermute_b32 v209, v198, v13
	ds_bpermute_b32 v210, v198, v14
	ds_bpermute_b32 v211, v198, v15
	s_waitcnt lgkmcnt(4)
	global_store_dwordx4 v191, v[216:219], s[18:19]
	global_store_dwordx4 v191, v[220:223], s[18:19] offset:256
	s_add_u32 s18, s18, 0x20000
	s_addc_u32 s19, s19, 0
	ds_bpermute_b32 v212, v198, v4
	ds_bpermute_b32 v213, v198, v5
	ds_bpermute_b32 v214, v198, v6
	ds_bpermute_b32 v215, v198, v7
	s_waitcnt lgkmcnt(0)
	global_store_dwordx4 v191, v[208:211], s[18:19]
	global_store_dwordx4 v191, v[212:215], s[18:19] offset:256
	s_andn2_b64 vcc, exec, s[2:3]
	s_mov_b64 s[2:3], -1
	s_cbranch_vccnz .LBB0_1172
	s_andn2_b64 vcc, exec, s[4:5]
	s_cbranch_vccnz .LBB0_1171
	s_barrier
	s_branch .LBB0_1171

.LBB0_1365:
	s_lshr_b32 s8, s21, 3
	s_mul_hi_u32 s9, s8, 0x6000
	s_mulk_i32 s8, 0x6000
	s_add_u32 s8, s37, s8
	s_addc_u32 s9, s39, s9
	v_mbcnt_lo_u32_b32 v176, -1, 0
	v_mbcnt_hi_u32_b32 v176, -1, v176
	v_and_b32_e32 v177, 15, v176
	v_lshrrev_b32_e32 v178, 2, v176
	v_sub_u32_e32 v177, v178, v177
	v_add_u32_e32 v177, v172, v177
	v_lshrrev_b32_e32 v180, 4, v176
	v_and_b32_e32 v179, 3, v176
	v_sub_u32_e32 v180, v179, v180
	v_lshl_add_u32 v182, v180, 5, v168
	v_lshrrev_b32_e32 v181, 2, v182
	v_lshl_add_u32 v183, v179, 4, v178
	v_lshlrev_b32_e32 v183, 2, v183
	s_add_u32 s100, s8, 0x5000
	s_addc_u32 s101, s9, 0
	global_load_dwordx4 v[72:75], v182, s[100:101]
	global_load_dwordx4 v[76:79], v182, s[100:101] offset:16
	global_load_dwordx4 v[36:39], v182, s[100:101] offset:512
	global_load_dwordx4 v[32:35], v182, s[100:101] offset:528
	ds_bpermute_b32 v208, v183, v124
	ds_bpermute_b32 v209, v183, v125
	ds_bpermute_b32 v210, v183, v126
	ds_bpermute_b32 v211, v183, v127
	ds_bpermute_b32 v212, v183, v120
	ds_bpermute_b32 v213, v183, v121
	ds_bpermute_b32 v214, v183, v122
	ds_bpermute_b32 v215, v183, v123
	s_waitcnt lgkmcnt(7)
	ds_bpermute_b32 v216, v183, v108
	ds_bpermute_b32 v217, v183, v109
	ds_bpermute_b32 v218, v183, v110
	ds_bpermute_b32 v219, v183, v111
	ds_bpermute_b32 v220, v183, v104
	ds_bpermute_b32 v221, v183, v105
	ds_bpermute_b32 v222, v183, v106
	ds_bpermute_b32 v223, v183, v107
	s_lshl_b32 s10, s21, 8
	s_mov_b64 s[12:13], s[74:75]
	s_mov_b64 s[100:101], s[74:75]
	v_add_u32_e32 v154, s10, v177
	v_lshl_add_u32 v154, v154, 10, v181
	v_lshlrev_b32_e32 v154, 2, v154
	s_waitcnt lgkmcnt(0)
	ds_bpermute_b32 v184, v183, v140
	ds_bpermute_b32 v185, v183, v141
	ds_bpermute_b32 v186, v183, v142
	ds_bpermute_b32 v187, v183, v143
	ds_bpermute_b32 v188, v183, v136
	ds_bpermute_b32 v189, v183, v137
	ds_bpermute_b32 v190, v183, v138
	ds_bpermute_b32 v191, v183, v139
	s_waitcnt lgkmcnt(7)
	ds_bpermute_b32 v192, v183, v132
	ds_bpermute_b32 v193, v183, v133
	ds_bpermute_b32 v194, v183, v134
	ds_bpermute_b32 v195, v183, v135
	ds_bpermute_b32 v196, v183, v128
	ds_bpermute_b32 v197, v183, v129
	ds_bpermute_b32 v198, v183, v130
	ds_bpermute_b32 v199, v183, v131
	s_waitcnt lgkmcnt(0)
	global_load_dwordx4 v[140:143], v154, s[12:13]
	global_load_dwordx4 v[136:139], v154, s[12:13] offset:16
	global_load_dwordx4 v[132:135], v154, s[12:13] offset:512
	global_load_dwordx4 v[128:131], v154, s[12:13] offset:528
	s_add_u32 s12, s12, 0x10000
	s_addc_u32 s13, s13, 0
	global_load_dwordx4 v[124:127], v154, s[12:13]
	global_load_dwordx4 v[120:123], v154, s[12:13] offset:16
	global_load_dwordx4 v[108:111], v154, s[12:13] offset:512
	global_load_dwordx4 v[104:107], v154, s[12:13] offset:528
	s_add_u32 s12, s12, 0x10000
	s_addc_u32 s13, s13, 0
	s_waitcnt vmcnt(4)
	v_pk_fma_f32 v[140:141], v[184:185], v[72:73], v[140:141]
	v_pk_fma_f32 v[142:143], v[186:187], v[74:75], v[142:143]
	v_pk_fma_f32 v[136:137], v[188:189], v[76:77], v[136:137]
	v_pk_fma_f32 v[138:139], v[190:191], v[78:79], v[138:139]
	v_pk_fma_f32 v[132:133], v[192:193], v[36:37], v[132:133]
	v_pk_fma_f32 v[134:135], v[194:195], v[38:39], v[134:135]
	v_pk_fma_f32 v[128:129], v[196:197], v[32:33], v[128:129]
	v_pk_fma_f32 v[130:131], v[198:199], v[34:35], v[130:131]
	ds_bpermute_b32 v184, v183, v116
	ds_bpermute_b32 v185, v183, v117
	ds_bpermute_b32 v186, v183, v118
	ds_bpermute_b32 v187, v183, v119
	ds_bpermute_b32 v188, v183, v112
	ds_bpermute_b32 v189, v183, v113
	ds_bpermute_b32 v190, v183, v114
	ds_bpermute_b32 v191, v183, v115
	global_store_dwordx4 v154, v[140:143], s[100:101]
	global_store_dwordx4 v154, v[136:139], s[100:101] offset:16
	global_store_dwordx4 v154, v[132:135], s[100:101] offset:512
	global_store_dwordx4 v154, v[128:131], s[100:101] offset:528
	s_add_u32 s100, s100, 0x10000
	s_addc_u32 s101, s101, 0
	s_waitcnt lgkmcnt(6)
	ds_bpermute_b32 v192, v183, v92
	ds_bpermute_b32 v193, v183, v93
	ds_bpermute_b32 v194, v183, v94
	ds_bpermute_b32 v195, v183, v95
	ds_bpermute_b32 v196, v183, v88
	ds_bpermute_b32 v197, v183, v89
	ds_bpermute_b32 v198, v183, v90
	ds_bpermute_b32 v199, v183, v91
	s_waitcnt lgkmcnt(0)
	global_load_dwordx4 v[116:119], v154, s[12:13]
	global_load_dwordx4 v[112:115], v154, s[12:13] offset:16
	global_load_dwordx4 v[92:95], v154, s[12:13] offset:512
	global_load_dwordx4 v[88:91], v154, s[12:13] offset:528
	s_add_u32 s12, s12, 0x10000
	s_addc_u32 s13, s13, 0
	s_waitcnt vmcnt(8)
	v_pk_fma_f32 v[124:125], v[208:209], v[72:73], v[124:125]
	v_pk_fma_f32 v[126:127], v[210:211], v[74:75], v[126:127]
	v_pk_fma_f32 v[120:121], v[212:213], v[76:77], v[120:121]
	v_pk_fma_f32 v[122:123], v[214:215], v[78:79], v[122:123]
	v_pk_fma_f32 v[108:109], v[216:217], v[36:37], v[108:109]
	v_pk_fma_f32 v[110:111], v[218:219], v[38:39], v[110:111]
	v_pk_fma_f32 v[104:105], v[220:221], v[32:33], v[104:105]
	v_pk_fma_f32 v[106:107], v[222:223], v[34:35], v[106:107]
	ds_bpermute_b32 v208, v183, v100
	ds_bpermute_b32 v209, v183, v101
	ds_bpermute_b32 v210, v183, v102
	ds_bpermute_b32 v211, v183, v103
	ds_bpermute_b32 v212, v183, v96
	ds_bpermute_b32 v213, v183, v97
	ds_bpermute_b32 v214, v183, v98
	ds_bpermute_b32 v215, v183, v99
	global_store_dwordx4 v154, v[124:127], s[100:101]
	global_store_dwordx4 v154, v[120:123], s[100:101] offset:16
	global_store_dwordx4 v154, v[108:111], s[100:101] offset:512
	global_store_dwordx4 v154, v[104:107], s[100:101] offset:528
	s_add_u32 s100, s100, 0x10000
	s_addc_u32 s101, s101, 0
	s_waitcnt lgkmcnt(6)
	ds_bpermute_b32 v216, v183, v84
	ds_bpermute_b32 v217, v183, v85
	ds_bpermute_b32 v218, v183, v86
	ds_bpermute_b32 v219, v183, v87
	ds_bpermute_b32 v220, v183, v80
	ds_bpermute_b32 v221, v183, v81
	ds_bpermute_b32 v222, v183, v82
	ds_bpermute_b32 v223, v183, v83
	s_waitcnt lgkmcnt(0)
	global_load_dwordx4 v[100:103], v154, s[12:13]
	global_load_dwordx4 v[96:99], v154, s[12:13] offset:16
	global_load_dwordx4 v[84:87], v154, s[12:13] offset:512
	global_load_dwordx4 v[80:83], v154, s[12:13] offset:528
	s_add_u32 s12, s12, 0x50000
	s_addc_u32 s13, s13, 0
	s_waitcnt vmcnt(8)
	v_pk_fma_f32 v[116:117], v[184:185], v[72:73], v[116:117]
	v_pk_fma_f32 v[118:119], v[186:187], v[74:75], v[118:119]
	v_pk_fma_f32 v[112:113], v[188:189], v[76:77], v[112:113]
	v_pk_fma_f32 v[114:115], v[190:191], v[78:79], v[114:115]
	v_pk_fma_f32 v[92:93], v[192:193], v[36:37], v[92:93]
	v_pk_fma_f32 v[94:95], v[194:195], v[38:39], v[94:95]
	v_pk_fma_f32 v[88:89], v[196:197], v[32:33], v[88:89]
	v_pk_fma_f32 v[90:91], v[198:199], v[34:35], v[90:91]
	ds_bpermute_b32 v184, v183, v68
	ds_bpermute_b32 v185, v183, v69
	ds_bpermute_b32 v186, v183, v70
	ds_bpermute_b32 v187, v183, v71
	ds_bpermute_b32 v188, v183, v64
	ds_bpermute_b32 v189, v183, v65
	ds_bpermute_b32 v190, v183, v66
	ds_bpermute_b32 v191, v183, v67
	global_store_dwordx4 v154, v[116:119], s[100:101]
	global_store_dwordx4 v154, v[112:115], s[100:101] offset:16
	global_store_dwordx4 v154, v[92:95], s[100:101] offset:512
	global_store_dwordx4 v154, v[88:91], s[100:101] offset:528
	s_add_u32 s100, s100, 0x10000
	s_addc_u32 s101, s101, 0
	s_waitcnt lgkmcnt(6)
	ds_bpermute_b32 v192, v183, v52
	ds_bpermute_b32 v193, v183, v53
	ds_bpermute_b32 v194, v183, v54
	ds_bpermute_b32 v195, v183, v55
	ds_bpermute_b32 v196, v183, v48
	ds_bpermute_b32 v197, v183, v49
	ds_bpermute_b32 v198, v183, v50
	ds_bpermute_b32 v199, v183, v51
	s_waitcnt lgkmcnt(0)
	global_load_dwordx4 v[68:71], v154, s[12:13]
	global_load_dwordx4 v[64:67], v154, s[12:13] offset:16
	global_load_dwordx4 v[52:55], v154, s[12:13] offset:512
	global_load_dwordx4 v[48:51], v154, s[12:13] offset:528
	s_add_u32 s12, s12, 0x10000
	s_addc_u32 s13, s13, 0
	s_waitcnt vmcnt(8)
	v_pk_fma_f32 v[100:101], v[208:209], v[72:73], v[100:101]
	v_pk_fma_f32 v[102:103], v[210:211], v[74:75], v[102:103]
	v_pk_fma_f32 v[96:97], v[212:213], v[76:77], v[96:97]
	v_pk_fma_f32 v[98:99], v[214:215], v[78:79], v[98:99]
	v_pk_fma_f32 v[84:85], v[216:217], v[36:37], v[84:85]
	v_pk_fma_f32 v[86:87], v[218:219], v[38:39], v[86:87]
	v_pk_fma_f32 v[80:81], v[220:221], v[32:33], v[80:81]
	v_pk_fma_f32 v[82:83], v[222:223], v[34:35], v[82:83]
	ds_bpermute_b32 v208, v183, v60
	ds_bpermute_b32 v209, v183, v61
	ds_bpermute_b32 v210, v183, v62
	ds_bpermute_b32 v211, v183, v63
	ds_bpermute_b32 v212, v183, v56
	ds_bpermute_b32 v213, v183, v57
	ds_bpermute_b32 v214, v183, v58
	ds_bpermute_b32 v215, v183, v59
	global_store_dwordx4 v154, v[100:103], s[100:101]
	global_store_dwordx4 v154, v[96:99], s[100:101] offset:16
	global_store_dwordx4 v154, v[84:87], s[100:101] offset:512
	global_store_dwordx4 v154, v[80:83], s[100:101] offset:528
	s_add_u32 s100, s100, 0x50000
	s_addc_u32 s101, s101, 0
	s_waitcnt lgkmcnt(6)
	ds_bpermute_b32 v216, v183, v44
	ds_bpermute_b32 v217, v183, v45
	ds_bpermute_b32 v218, v183, v46
	ds_bpermute_b32 v219, v183, v47
	ds_bpermute_b32 v220, v183, v40
	ds_bpermute_b32 v221, v183, v41
	ds_bpermute_b32 v222, v183, v42
	ds_bpermute_b32 v223, v183, v43
	s_waitcnt lgkmcnt(0)
	global_load_dwordx4 v[60:63], v154, s[12:13]
	global_load_dwordx4 v[56:59], v154, s[12:13] offset:16
	global_load_dwordx4 v[44:47], v154, s[12:13] offset:512
	global_load_dwordx4 v[40:43], v154, s[12:13] offset:528
	s_add_u32 s12, s12, 0x10000
	s_addc_u32 s13, s13, 0
	s_waitcnt vmcnt(8)
	v_pk_fma_f32 v[68:69], v[184:185], v[72:73], v[68:69]
	v_pk_fma_f32 v[70:71], v[186:187], v[74:75], v[70:71]
	v_pk_fma_f32 v[64:65], v[188:189], v[76:77], v[64:65]
	v_pk_fma_f32 v[66:67], v[190:191], v[78:79], v[66:67]
	v_pk_fma_f32 v[52:53], v[192:193], v[36:37], v[52:53]
	v_pk_fma_f32 v[54:55], v[194:195], v[38:39], v[54:55]
	v_pk_fma_f32 v[48:49], v[196:197], v[32:33], v[48:49]
	v_pk_fma_f32 v[50:51], v[198:199], v[34:35], v[50:51]
	ds_bpermute_b32 v184, v183, v28
	ds_bpermute_b32 v185, v183, v29
	ds_bpermute_b32 v186, v183, v30
	ds_bpermute_b32 v187, v183, v31
	ds_bpermute_b32 v188, v183, v24
	ds_bpermute_b32 v189, v183, v25
	ds_bpermute_b32 v190, v183, v26
	ds_bpermute_b32 v191, v183, v27
	global_store_dwordx4 v154, v[68:71], s[100:101]
	global_store_dwordx4 v154, v[64:67], s[100:101] offset:16
	global_store_dwordx4 v154, v[52:55], s[100:101] offset:512
	global_store_dwordx4 v154, v[48:51], s[100:101] offset:528
	s_add_u32 s100, s100, 0x10000
	s_addc_u32 s101, s101, 0
	s_waitcnt lgkmcnt(6)
	ds_bpermute_b32 v192, v183, v20
	ds_bpermute_b32 v193, v183, v21
	ds_bpermute_b32 v194, v183, v22
	ds_bpermute_b32 v195, v183, v23
	ds_bpermute_b32 v196, v183, v16
	ds_bpermute_b32 v197, v183, v17
	ds_bpermute_b32 v198, v183, v18
	ds_bpermute_b32 v199, v183, v19
	s_waitcnt lgkmcnt(0)
	global_load_dwordx4 v[28:31], v154, s[12:13]
	global_load_dwordx4 v[24:27], v154, s[12:13] offset:16
	global_load_dwordx4 v[20:23], v154, s[12:13] offset:512
	global_load_dwordx4 v[16:19], v154, s[12:13] offset:528
	s_add_u32 s12, s12, 0x10000
	s_addc_u32 s13, s13, 0
	s_waitcnt vmcnt(8)
	v_pk_fma_f32 v[60:61], v[208:209], v[72:73], v[60:61]
	v_pk_fma_f32 v[62:63], v[210:211], v[74:75], v[62:63]
	v_pk_fma_f32 v[56:57], v[212:213], v[76:77], v[56:57]
	v_pk_fma_f32 v[58:59], v[214:215], v[78:79], v[58:59]
	v_pk_fma_f32 v[44:45], v[216:217], v[36:37], v[44:45]
	v_pk_fma_f32 v[46:47], v[218:219], v[38:39], v[46:47]
	v_pk_fma_f32 v[40:41], v[220:221], v[32:33], v[40:41]
	v_pk_fma_f32 v[42:43], v[222:223], v[34:35], v[42:43]
	ds_bpermute_b32 v208, v183, v12
	ds_bpermute_b32 v209, v183, v13
	ds_bpermute_b32 v210, v183, v14
	ds_bpermute_b32 v211, v183, v15
	ds_bpermute_b32 v212, v183, v8
	ds_bpermute_b32 v213, v183, v9
	ds_bpermute_b32 v214, v183, v10
	ds_bpermute_b32 v215, v183, v11
	global_store_dwordx4 v154, v[60:63], s[100:101]
	global_store_dwordx4 v154, v[56:59], s[100:101] offset:16
	global_store_dwordx4 v154, v[44:47], s[100:101] offset:512
	global_store_dwordx4 v154, v[40:43], s[100:101] offset:528
	s_add_u32 s100, s100, 0x10000
	s_addc_u32 s101, s101, 0
	s_waitcnt lgkmcnt(6)
	ds_bpermute_b32 v216, v183, v4
	ds_bpermute_b32 v217, v183, v5
	ds_bpermute_b32 v218, v183, v6
	ds_bpermute_b32 v219, v183, v7
	ds_bpermute_b32 v220, v183, v0
	ds_bpermute_b32 v221, v183, v1
	ds_bpermute_b32 v222, v183, v2
	ds_bpermute_b32 v223, v183, v3
	s_waitcnt lgkmcnt(0)
	global_load_dwordx4 v[12:15], v154, s[12:13]
	global_load_dwordx4 v[8:11], v154, s[12:13] offset:16
	global_load_dwordx4 v[4:7], v154, s[12:13] offset:512
	global_load_dwordx4 v[0:3], v154, s[12:13] offset:528
	s_waitcnt vmcnt(8)
	v_pk_fma_f32 v[28:29], v[184:185], v[72:73], v[28:29]
	v_pk_fma_f32 v[30:31], v[186:187], v[74:75], v[30:31]
	v_pk_fma_f32 v[24:25], v[188:189], v[76:77], v[24:25]
	v_pk_fma_f32 v[26:27], v[190:191], v[78:79], v[26:27]
	v_pk_fma_f32 v[20:21], v[192:193], v[36:37], v[20:21]
	v_pk_fma_f32 v[22:23], v[194:195], v[38:39], v[22:23]
	v_pk_fma_f32 v[16:17], v[196:197], v[32:33], v[16:17]
	v_pk_fma_f32 v[18:19], v[198:199], v[34:35], v[18:19]
	global_store_dwordx4 v154, v[28:31], s[100:101]
	global_store_dwordx4 v154, v[24:27], s[100:101] offset:16
	global_store_dwordx4 v154, v[20:23], s[100:101] offset:512
	global_store_dwordx4 v154, v[16:19], s[100:101] offset:528
	s_add_u32 s100, s100, 0x10000
	s_addc_u32 s101, s101, 0
	s_waitcnt vmcnt(4)
	v_pk_fma_f32 v[12:13], v[208:209], v[72:73], v[12:13]
	v_pk_fma_f32 v[14:15], v[210:211], v[74:75], v[14:15]
	v_pk_fma_f32 v[8:9], v[212:213], v[76:77], v[8:9]
	v_pk_fma_f32 v[10:11], v[214:215], v[78:79], v[10:11]
	v_pk_fma_f32 v[4:5], v[216:217], v[36:37], v[4:5]
	v_pk_fma_f32 v[6:7], v[218:219], v[38:39], v[6:7]
	v_pk_fma_f32 v[0:1], v[220:221], v[32:33], v[0:1]
	v_pk_fma_f32 v[2:3], v[222:223], v[34:35], v[2:3]
	global_store_dwordx4 v154, v[12:15], s[100:101]
	global_store_dwordx4 v154, v[8:11], s[100:101] offset:16
	global_store_dwordx4 v154, v[4:7], s[100:101] offset:512
	global_store_dwordx4 v154, v[0:3], s[100:101] offset:528
	s_mov_b64 s[8:9], -1
	s_andn2_b64 vcc, exec, s[6:7]
	s_cbranch_vccnz .LBB0_1360
	s_andn2_b64 vcc, exec, s[0:1]
	s_cbranch_vccnz .LBB0_1359
	s_barrier
	s_branch .LBB0_1359
